# nt hint on the final f32 output stores of phase 14 only
# speedup vs baseline: 1.0032x; 1.0032x over previous
; template <bool FIRST, bool HAS_NEXT, bool CTXSPLIT = false>
; __device__ __forceinline__ void phase_rows(const KArgs& a, int row_begin, int nrows, int CH, const float* mods_cur, int gate_ch, const float* g_post, const float* mods_nxt, int sh_ch, const float* g_pre, int lane, int wave) {
;     ...
;     for (int ch = gw; ch < nrows / CH; ch += NGW) {
;         const int r0 = row_begin + ch * CH; const int ms = r0 < MLAT ? r0 / SEQ : 2;
;         f32x4 gg[4], gs[4], sh[4];
; #pragma unroll
;         for (int j = 0; j < 4; ++j) { const int col = RCOL(j);
;             gg[j] = *(const f32x4*)(mods_cur + ms * MODW + gate_ch * DM + col) * *(const f32x4*)(g_post + col);
;             if (HAS_NEXT) { gs[j] = *(const f32x4*)(g_pre + col) * (1.0f + *(const f32x4*)(mods_nxt + ms * MODW + (sh_ch + 1) * DM + col)); sh[j] = *(const f32x4*)(mods_nxt + ms * MODW + sh_ch * DM + col); }
;         }
;         for (int rr = 0; rr < CH; rr += 2) {
;             f32x4 xv[2][4], yv[2][4]; float ss[2], s2[2];
; #pragma unroll
;             for (int q = 0; q < 2; ++q) { const int r = r0 + rr + q;
;                 const float* xin = r < MLAT ? a.x + (size_t)r * DM : a.ctx + (size_t)(r - MLAT) * DM;
;                 const bf16r* ay = AY + (size_t)r * DM; ss[q] = 0.f;
; #pragma unroll
;                 for (int jp = 0; jp < 2; ++jp) { const int c8 = 512 * jp + 8 * lane;
;                     if (FIRST) { xv[q][2 * jp] = __builtin_nontemporal_load((const f32x4*)(xin + c8)); xv[q][2 * jp + 1] = __builtin_nontemporal_load((const f32x4*)(xin + c8 + 4)); }
;                     else { const u32x4 xw = *(const u32x4*)(XB + (size_t)r * DM + c8); UNPK(xw, xv[q][2 * jp], xv[q][2 * jp + 1]); }
;                     if (CTXSPLIT && r >= MLAT) {
; #pragma unroll
;                         for (int h = 0; h < 2; ++h) { const float* pp = (const float*)a.out + (size_t)(r - MLAT) * DM + c8 + 4 * h; f32x4 acc4 = *(const f32x4*)pp;
; #pragma unroll
;                             for (int ks = 1; ks < KSPLIT; ++ks) acc4 += *(const f32x4*)(pp + (size_t)ks * MCTX * DM);
;                             yv[q][2 * jp + h] = acc4; } }
;                     else { const u32x4 w = *(const u32x4*)(ay + c8); UNPK(w, yv[q][2 * jp], yv[q][2 * jp + 1]); } } }
; #pragma unroll
;             for (int q = 0; q < 2; ++q)
; #pragma unroll
.LBB0_1185:
	s_ashr_i32 s0, s20, 31
	s_lshr_b32 s0, s0, 22
	s_add_i32 s0, s20, s0
	s_lshr_b32 s0, s0, 10
	s_mulk_i32 s0, 0x1800
	s_ashr_i32 s1, s0, 31
	s_lshl_b64 s[0:1], s[0:1], 2
	s_add_u32 s0, s84, s0
	s_addc_u32 s1, s85, s1
	s_add_u32 s0, s0, 0x5000
	s_addc_u32 s1, s1, 0
	s_add_i32 s2, s6, -7
	s_add_i32 s4, s6, -6
	s_ashr_i32 s3, s2, 31
	s_ashr_i32 s5, s4, 31
	s_lshl_b64 s[24:25], s[2:3], 11
	s_lshl_b64 s[26:27], s[4:5], 11
	v_lshl_add_u64 v[120:121], v[20:21], 0, s[24:25]
	v_lshl_add_u64 v[122:123], v[22:23], 0, s[24:25]
	global_load_dwordx4 v[0:3], v[16:17], off offset:16
	global_load_dwordx4 v[4:7], v[16:17], off
	global_load_dwordx4 v[8:11], v[18:19], off offset:16
	global_load_dwordx4 v[12:15], v[18:19], off
	global_load_dwordx4 v[76:79], v72, s[0:1] offset:16
	global_load_dwordx4 v[80:83], v72, s[0:1]
	global_load_dwordx4 v[84:87], v73, s[0:1] offset:16
	global_load_dwordx4 v[88:91], v73, s[0:1]
	v_lshl_add_u64 v[124:125], v[20:21], 0, s[26:27]
	v_lshl_add_u64 v[126:127], v[22:23], 0, s[26:27]
	global_load_dwordx4 v[92:95], v[120:121], off
	global_load_dwordx4 v[96:99], v[120:121], off offset:1024
	global_load_dwordx4 v[100:103], v[122:123], off offset:1024
	global_load_dwordx4 v[104:107], v[124:125], off
	global_load_dwordx4 v[108:111], v[124:125], off offset:1024
	global_load_dwordx4 v[112:115], v[126:127], off offset:1024
	global_load_dwordx4 v[116:119], v[122:123], off
	s_nop 0
	global_load_dwordx4 v[120:123], v[126:127], off
	s_add_i32 s16, s6, -1
	s_ashr_i32 s7, s6, 31
	s_ashr_i32 s17, s16, 31
	s_lshl_b64 s[0:1], s[6:7], 11
	v_lshl_add_u64 v[30:31], v[20:21], 0, s[0:1]
	v_lshl_add_u64 v[32:33], v[22:23], 0, s[0:1]
	s_lshl_b64 s[0:1], s[16:17], 12
	v_lshl_add_u64 v[28:29], v[24:25], 0, s[0:1]
	s_lshl_b64 s[2:3], s[2:3], 12
	s_lshl_b64 s[4:5], s[4:5], 12
	v_lshl_add_u64 v[64:65], v[24:25], 0, s[2:3]
	v_lshl_add_u64 v[62:63], v[24:25], 0, s[4:5]
	s_add_i32 s8, s6, -5
	s_add_i32 s10, s6, -4
	s_ashr_i32 s9, s8, 31
	s_ashr_i32 s11, s10, 31
	s_lshl_b64 s[28:29], s[8:9], 11
	s_lshl_b64 s[30:31], s[10:11], 11
	v_lshl_add_u64 v[56:57], v[20:21], 0, s[28:29]
	v_lshl_add_u64 v[54:55], v[22:23], 0, s[28:29]
	v_lshl_add_u64 v[58:59], v[20:21], 0, s[30:31]
	v_lshl_add_u64 v[60:61], v[22:23], 0, s[30:31]
	s_add_i32 s12, s6, -3
	s_lshl_b64 s[8:9], s[8:9], 12
	s_add_i32 s14, s6, -2
	s_ashr_i32 s13, s12, 31
	s_lshl_b64 s[10:11], s[10:11], 12
	v_lshl_add_u64 v[52:53], v[24:25], 0, s[8:9]
	s_ashr_i32 s15, s14, 31
	s_lshl_b64 s[34:35], s[12:13], 11
	v_lshl_add_u64 v[50:51], v[24:25], 0, s[10:11]
	s_lshl_b64 s[36:37], s[14:15], 11
	v_lshl_add_u64 v[42:43], v[20:21], 0, s[34:35]
	v_lshl_add_u64 v[46:47], v[22:23], 0, s[34:35]
	v_lshl_add_u64 v[44:45], v[20:21], 0, s[36:37]
	v_lshl_add_u64 v[48:49], v[22:23], 0, s[36:37]
	s_lshl_b64 s[12:13], s[12:13], 12
	s_lshl_b64 s[14:15], s[14:15], 12
	v_lshl_add_u64 v[40:41], v[24:25], 0, s[12:13]
	s_lshl_b64 s[38:39], s[16:17], 11
	v_lshl_add_u64 v[38:39], v[24:25], 0, s[14:15]
	v_lshl_add_u64 v[34:35], v[20:21], 0, s[38:39]
	v_lshl_add_u64 v[36:37], v[22:23], 0, s[38:39]
	s_add_i32 s20, s20, s21
	s_lshl_b64 s[22:23], s[6:7], 12
	s_add_i32 s6, s6, s18
	v_lshl_add_u64 v[26:27], v[24:25], 0, s[22:23]
	s_cmpk_lt_i32 s20, 0x800
	s_waitcnt vmcnt(0)
	v_lshlrev_b32_e32 v132, 16, v100
	v_and_b32_e32 v133, 0xffff0000, v100
	v_lshlrev_b32_e32 v100, 16, v101
	v_and_b32_e32 v101, 0xffff0000, v101
	v_lshlrev_b32_e32 v128, 16, v116
	v_and_b32_e32 v129, 0xffff0000, v116
	v_lshlrev_b32_e32 v116, 16, v117
	v_lshlrev_b32_e32 v131, 16, v119
	v_lshlrev_b32_e32 v130, 16, v118
	v_and_b32_e32 v119, 0xffff0000, v119
	v_and_b32_e32 v118, 0xffff0000, v118
	v_and_b32_e32 v117, 0xffff0000, v117
	v_lshlrev_b32_e32 v134, 16, v120
	v_and_b32_e32 v135, 0xffff0000, v120
	v_lshlrev_b32_e32 v120, 16, v121
	v_lshlrev_b32_e32 v137, 16, v123
	v_lshlrev_b32_e32 v136, 16, v122
	v_and_b32_e32 v123, 0xffff0000, v123
	v_and_b32_e32 v122, 0xffff0000, v122
	v_mul_f32_e32 v140, v128, v128
	v_mul_f32_e32 v142, v116, v116
	v_pk_mul_f32 v[144:145], v[118:119], v[118:119]
	v_and_b32_e32 v121, 0xffff0000, v121
	v_lshlrev_b32_e32 v138, 16, v112
	v_and_b32_e32 v139, 0xffff0000, v112
	v_lshlrev_b32_e32 v112, 16, v113
	v_mul_f32_e32 v146, v132, v132
	v_mul_f32_e32 v148, v100, v100
	v_mul_f32_e32 v152, v134, v134
	v_mul_f32_e32 v154, v120, v120
	v_pk_mul_f32 v[156:157], v[122:123], v[122:123]
	v_mov_b32_e32 v164, v130
	v_mov_b32_e32 v165, v118
	v_mov_b32_e32 v118, v131
	v_pk_fma_f32 v[140:141], v[128:129], v[128:129], v[140:141] op_sel_hi:[1,1,0]
	v_pk_fma_f32 v[142:143], v[116:117], v[116:117], v[142:143] op_sel_hi:[1,1,0]
	v_pk_fma_f32 v[130:131], v[130:131], v[130:131], v[144:145]
	v_pk_mul_f32 v[6:7], v[82:83], v[6:7]
	v_pk_mul_f32 v[4:5], v[80:81], v[4:5]
	v_pk_mul_f32 v[2:3], v[78:79], v[2:3]
	v_pk_mul_f32 v[0:1], v[76:77], v[0:1]
	v_lshlrev_b32_e32 v76, 16, v92
	v_and_b32_e32 v77, 0xffff0000, v92
	v_lshlrev_b32_e32 v78, 16, v93
	v_and_b32_e32 v79, 0xffff0000, v93
	v_lshlrev_b32_e32 v80, 16, v94
	v_and_b32_e32 v81, 0xffff0000, v94
	v_lshlrev_b32_e32 v82, 16, v95
	v_and_b32_e32 v83, 0xffff0000, v95
	v_lshlrev_b32_e32 v92, 16, v102
	v_and_b32_e32 v93, 0xffff0000, v102
	v_lshlrev_b32_e32 v94, 16, v103
	v_and_b32_e32 v95, 0xffff0000, v103
	v_and_b32_e32 v113, 0xffff0000, v113
	v_mul_f32_e32 v158, v138, v138
	v_mul_f32_e32 v160, v112, v112
	v_mov_b32_e32 v166, v136
	v_mov_b32_e32 v167, v122
	v_mov_b32_e32 v122, v137
	v_pk_fma_f32 v[144:145], v[132:133], v[132:133], v[146:147] op_sel_hi:[1,1,0]
	v_pk_fma_f32 v[146:147], v[100:101], v[100:101], v[148:149] op_sel_hi:[1,1,0]
	v_pk_fma_f32 v[148:149], v[134:135], v[134:135], v[152:153] op_sel_hi:[1,1,0]
; template <bool FIRST, bool HAS_NEXT, bool CTXSPLIT = false>
; __device__ __forceinline__ void phase_rows(const KArgs& a, int row_begin, int nrows, int CH, const float* mods_cur, int gate_ch, const float* g_post, const float* mods_nxt, int sh_ch, const float* g_pre, int lane, int wave) {
;     ...
;                 for (int j = 0; j < 4; ++j) ss[q] += (yv[q][j].x * yv[q][j].x + yv[q][j].y * yv[q][j].y) + (yv[q][j].z * yv[q][j].z + yv[q][j].w * yv[q][j].w);
; #pragma unroll
;             for (int o = 1; o < 64; o <<= 1) { ss[0] += __shfl_xor(ss[0], o); ss[1] += __shfl_xor(ss[1], o); }
; #pragma unroll
;             for (int q = 0; q < 2; ++q) { const int r = r0 + rr + q;
;                 const float ry = 1.0f / sqrtf(ss[q] * (1.0f / DM) + EPS); s2[q] = 0.f;
; #pragma unroll
;                 for (int j = 0; j < 4; ++j) { xv[q][j] = xv[q][j] + gg[j] * (yv[q][j] * ry);
	v_pk_fma_f32 v[152:153], v[120:121], v[120:121], v[154:155] op_sel_hi:[1,1,0]
	v_pk_fma_f32 v[136:137], v[136:137], v[136:137], v[156:157]
	v_pk_add_f32 v[130:131], v[130:131], v[130:131] op_sel_hi:[0,1]
	v_pk_add_f32 v[140:141], v[140:141], v[142:143]
	v_lshlrev_b32_e32 v126, 16, v114
	v_and_b32_e32 v127, 0xffff0000, v114
	v_lshlrev_b32_e32 v114, 16, v115
	v_and_b32_e32 v115, 0xffff0000, v115
	v_mul_f32_e32 v150, v92, v92
	v_pk_fma_f32 v[154:155], v[138:139], v[138:139], v[158:159] op_sel_hi:[1,1,0]
	v_pk_fma_f32 v[156:157], v[112:113], v[112:113], v[160:161] op_sel_hi:[1,1,0]
	v_mul_f32_e32 v144, v94, v94
	v_mul_f32_e32 v146, v95, v95
	v_pk_add_f32 v[136:137], v[136:137], v[136:137] op_sel_hi:[0,1]
	v_pk_add_f32 v[142:143], v[148:149], v[152:153]
	v_mul_f32_e32 v130, v93, v93
	v_mov_b32_e32 v151, v141
	v_mul_f32_e32 v162, v126, v126
	v_mul_f32_e32 v154, v114, v114
	v_mul_f32_e32 v156, v115, v115
	v_pk_add_f32 v[140:141], v[144:145], v[146:147]
	v_mul_f32_e32 v136, v127, v127
	v_mov_b32_e32 v163, v143
	v_pk_add_f32 v[130:131], v[150:151], v[130:131]
	v_pk_add_f32 v[142:143], v[154:155], v[156:157]
	v_pk_add_f32 v[136:137], v[162:163], v[136:137]
	v_pk_add_f32 v[130:131], v[130:131], v[140:141]
	v_pk_add_f32 v[136:137], v[136:137], v[142:143]
	v_add_f32_e32 v130, v130, v131
	v_add_f32_e32 v131, v136, v137
	ds_bpermute_b32 v136, v66, v130
	ds_bpermute_b32 v137, v66, v131
	v_pk_mul_f32 v[14:15], v[90:91], v[14:15]
	v_pk_mul_f32 v[12:13], v[88:89], v[12:13]
	v_pk_mul_f32 v[10:11], v[86:87], v[10:11]
	s_waitcnt lgkmcnt(1)
	v_add_f32_e32 v130, v130, v136
	s_waitcnt lgkmcnt(0)
	v_add_f32_e32 v131, v131, v137
	ds_bpermute_b32 v136, v67, v130
	ds_bpermute_b32 v137, v67, v131
	v_pk_mul_f32 v[8:9], v[84:85], v[8:9]
	v_lshlrev_b32_e32 v88, 16, v98
	v_and_b32_e32 v89, 0xffff0000, v98
	s_waitcnt lgkmcnt(1)
	v_add_f32_e32 v130, v130, v136
	s_waitcnt lgkmcnt(0)
	v_add_f32_e32 v131, v131, v137
	ds_bpermute_b32 v136, v68, v130
	ds_bpermute_b32 v137, v68, v131
	v_lshlrev_b32_e32 v90, 16, v99
	v_and_b32_e32 v91, 0xffff0000, v99
	v_lshlrev_b32_e32 v84, 16, v96
	s_waitcnt lgkmcnt(1)
	v_add_f32_e32 v130, v130, v136
	s_waitcnt lgkmcnt(0)
	v_add_f32_e32 v131, v131, v137
	ds_bpermute_b32 v136, v69, v130
	ds_bpermute_b32 v137, v69, v131
	v_and_b32_e32 v85, 0xffff0000, v96
	v_lshlrev_b32_e32 v86, 16, v97
	v_and_b32_e32 v87, 0xffff0000, v97
	s_waitcnt lgkmcnt(1)
	v_add_f32_e32 v130, v130, v136
	s_waitcnt lgkmcnt(0)
	v_add_f32_e32 v131, v131, v137
	ds_bpermute_b32 v136, v70, v130
	ds_bpermute_b32 v137, v70, v131
	v_lshlrev_b32_e32 v96, 16, v104
	v_and_b32_e32 v97, 0xffff0000, v104
	v_lshlrev_b32_e32 v98, 16, v105
	s_waitcnt lgkmcnt(1)
	v_add_f32_e32 v130, v130, v136
	s_waitcnt lgkmcnt(0)
	v_add_f32_e32 v131, v131, v137
	ds_bpermute_b32 v136, v71, v130
	ds_bpermute_b32 v137, v71, v131
	v_and_b32_e32 v99, 0xffff0000, v105
	v_lshlrev_b32_e32 v102, 16, v106
	v_and_b32_e32 v103, 0xffff0000, v106
	s_waitcnt lgkmcnt(1)
	v_add_f32_e32 v130, v130, v136
	s_waitcnt lgkmcnt(0)
	v_add_f32_e32 v131, v131, v137
	v_fmamk_f32 v130, v130, 0x3a800000, v74
	v_fmamk_f32 v131, v131, 0x3a800000, v74
	v_mul_f32_e32 v136, 0x4f800000, v130
	v_cmp_gt_f32_e64 s[0:1], s19, v130
	v_mul_f32_e32 v137, 0x4f800000, v131
	v_cmp_gt_f32_e32 vcc, s19, v131
	v_cndmask_b32_e64 v130, v130, v136, s[0:1]
	v_sqrt_f32_e32 v136, v130
	v_cndmask_b32_e32 v131, v131, v137, vcc
	v_sqrt_f32_e32 v137, v131
	v_lshlrev_b32_e32 v104, 16, v107
	v_add_u32_e32 v140, -1, v136
	v_add_u32_e32 v141, 1, v136
	v_add_u32_e32 v142, -1, v137
	v_fma_f32 v144, -v140, v136, v130
	v_add_u32_e32 v143, 1, v137
	v_fma_f32 v145, -v141, v136, v130
	v_fma_f32 v146, -v142, v137, v131
	v_cmp_ge_f32_e64 s[2:3], 0, v144
	v_fma_f32 v147, -v143, v137, v131
	v_cmp_lt_f32_e64 s[4:5], 0, v145
	v_cndmask_b32_e64 v136, v136, v140, s[2:3]
	v_cmp_ge_f32_e64 s[2:3], 0, v146
	v_cndmask_b32_e64 v136, v136, v141, s[4:5]
	v_mul_f32_e32 v140, 0x37800000, v136
	v_cndmask_b32_e64 v137, v137, v142, s[2:3]
	v_cmp_lt_f32_e64 s[2:3], 0, v147
	v_cndmask_b32_e64 v136, v136, v140, s[0:1]
	v_cmp_class_f32_e64 s[0:1], v130, v75
	v_cndmask_b32_e64 v137, v137, v143, s[2:3]
	v_mul_f32_e32 v141, 0x37800000, v137
	v_cndmask_b32_e32 v137, v137, v141, vcc
	v_cmp_class_f32_e32 vcc, v131, v75
	v_cndmask_b32_e64 v130, v136, v130, s[0:1]
	v_div_scale_f32 v136, s[0:1], v130, v130, 1.0
	v_cndmask_b32_e32 v131, v137, v131, vcc
	v_div_scale_f32 v140, s[0:1], v131, v131, 1.0
	v_rcp_f32_e32 v142, v136
	v_rcp_f32_e32 v143, v140
	v_div_scale_f32 v137, vcc, 1.0, v130, 1.0
	v_fma_f32 v144, -v136, v142, 1.0
	v_fma_f32 v145, -v140, v143, 1.0
	v_fmac_f32_e32 v142, v144, v142
	v_div_scale_f32 v141, s[0:1], 1.0, v131, 1.0
	v_fmac_f32_e32 v143, v145, v143
	v_mul_f32_e32 v144, v137, v142
	v_mul_f32_e32 v145, v141, v143
	v_fma_f32 v146, -v136, v144, v137
	v_fma_f32 v147, -v140, v145, v141
	v_fmac_f32_e32 v144, v146, v142
	v_fmac_f32_e32 v145, v147, v143
	v_fma_f32 v136, -v136, v144, v137
	v_fma_f32 v137, -v140, v145, v141
	v_div_fmas_f32 v136, v136, v142, v144
	s_mov_b64 vcc, s[0:1]
	v_div_fixup_f32 v130, v136, v130, 1.0
	v_div_fmas_f32 v140, v137, v143, v145
	v_pk_mul_f32 v[128:129], v[130:131], v[128:129] op_sel_hi:[0,1]
	v_pk_mul_f32 v[116:117], v[130:131], v[116:117] op_sel_hi:[0,1]
	v_pk_mul_f32 v[136:137], v[130:131], v[164:165] op_sel_hi:[0,1]
	v_pk_mul_f32 v[118:119], v[130:131], v[118:119] op_sel_hi:[0,1]
	v_pk_mul_f32 v[132:133], v[130:131], v[132:133] op_sel_hi:[0,1]
	v_pk_mul_f32 v[100:101], v[130:131], v[100:101] op_sel_hi:[0,1]
	v_pk_mul_f32 v[92:93], v[130:131], v[92:93] op_sel_hi:[0,1]
	v_pk_mul_f32 v[94:95], v[130:131], v[94:95] op_sel_hi:[0,1]
	v_div_fixup_f32 v130, v140, v131, 1.0
; template <bool FIRST, bool HAS_NEXT, bool CTXSPLIT = false>
; __device__ __forceinline__ void phase_rows(const KArgs& a, int row_begin, int nrows, int CH, const float* mods_cur, int gate_ch, const float* g_post, const float* mods_nxt, int sh_ch, const float* g_pre, int lane, int wave) {
;     ...
;             for (int q = 0; q < 2; ++q) { const int r = r0 + rr + q;
;                 const float* xin = r < MLAT ? a.x + (size_t)r * DM : a.ctx + (size_t)(r - MLAT) * DM;
;                 const bf16r* ay = AY + (size_t)r * DM; ss[q] = 0.f;
; #pragma unroll
;                 for (int jp = 0; jp < 2; ++jp) { const int c8 = 512 * jp + 8 * lane;
;                     if (FIRST) { xv[q][2 * jp] = __builtin_nontemporal_load((const f32x4*)(xin + c8)); xv[q][2 * jp + 1] = __builtin_nontemporal_load((const f32x4*)(xin + c8 + 4)); }
;                     else { const u32x4 xw = *(const u32x4*)(XB + (size_t)r * DM + c8); UNPK(xw, xv[q][2 * jp], xv[q][2 * jp + 1]); }
;                     if (CTXSPLIT && r >= MLAT) {
; #pragma unroll
;                         for (int h = 0; h < 2; ++h) { const float* pp = (const float*)a.out + (size_t)(r - MLAT) * DM + c8 + 4 * h; f32x4 acc4 = *(const f32x4*)pp;
; #pragma unroll
;                             for (int ks = 1; ks < KSPLIT; ++ks) acc4 += *(const f32x4*)(pp + (size_t)ks * MCTX * DM);
;                             yv[q][2 * jp + h] = acc4; } }
;     ...
;             for (int q = 0; q < 2; ++q) { const int r = r0 + rr + q;
;                 const float ry = 1.0f / sqrtf(ss[q] * (1.0f / DM) + EPS); s2[q] = 0.f;
; #pragma unroll
;                 for (int j = 0; j < 4; ++j) { xv[q][j] = xv[q][j] + gg[j] * (yv[q][j] * ry);
;                     s2[q] += (xv[q][j].x * xv[q][j].x + xv[q][j].y * xv[q][j].y) + (xv[q][j].z * xv[q][j].z + xv[q][j].w * xv[q][j].w); }
; #pragma unroll
;                 for (int jp = 0; jp < 2; ++jp) { const int c8 = 512 * jp + 8 * lane; const f32x4 lo4 = xv[q][2 * jp], hi4 = xv[q][2 * jp + 1];
;                     if (HAS_NEXT) { u32x4 xo; xo.x = pk2(lo4.x, lo4.y); xo.y = pk2(lo4.z, lo4.w); xo.z = pk2(hi4.x, hi4.y); xo.w = pk2(hi4.z, hi4.w); *(u32x4*)(XB + (size_t)r * DM + c8) = xo; }
;                     else { *(f32x4*)(a.out + (size_t)r * DM + c8) = lo4; *(f32x4*)(a.out + (size_t)r * DM + c8 + 4) = hi4; } } }
	v_pk_fma_f32 v[78:79], v[6:7], v[116:117], v[78:79]
	v_pk_fma_f32 v[76:77], v[4:5], v[128:129], v[76:77]
	v_pk_fma_f32 v[90:91], v[10:11], v[94:95], v[90:91]
	v_pk_fma_f32 v[88:89], v[8:9], v[92:93], v[88:89]
	v_pk_mul_f32 v[92:93], v[130:131], v[134:135] op_sel_hi:[0,1]
	v_pk_mul_f32 v[94:95], v[130:131], v[120:121] op_sel_hi:[0,1]
	v_and_b32_e32 v105, 0xffff0000, v107
	v_lshlrev_b32_e32 v106, 16, v108
	v_and_b32_e32 v107, 0xffff0000, v108
	v_lshlrev_b32_e32 v108, 16, v109
	v_and_b32_e32 v109, 0xffff0000, v109
	v_lshlrev_b32_e32 v124, 16, v110
	v_and_b32_e32 v125, 0xffff0000, v110
	v_lshlrev_b32_e32 v110, 16, v111
	v_and_b32_e32 v111, 0xffff0000, v111
	v_pk_fma_f32 v[82:83], v[2:3], v[118:119], v[82:83]
	v_pk_fma_f32 v[80:81], v[0:1], v[136:137], v[80:81]
	v_pk_fma_f32 v[86:87], v[14:15], v[100:101], v[86:87]
	v_pk_fma_f32 v[84:85], v[12:13], v[132:133], v[84:85]
	v_pk_mul_f32 v[100:101], v[130:131], v[166:167] op_sel_hi:[0,1]
	v_pk_mul_f32 v[116:117], v[130:131], v[122:123] op_sel_hi:[0,1]
	v_pk_mul_f32 v[118:119], v[130:131], v[138:139] op_sel_hi:[0,1]
	v_pk_mul_f32 v[112:113], v[130:131], v[112:113] op_sel_hi:[0,1]
	v_pk_mul_f32 v[120:121], v[130:131], v[126:127] op_sel_hi:[0,1]
	v_pk_mul_f32 v[114:115], v[130:131], v[114:115] op_sel_hi:[0,1]
	global_store_dwordx4 v[64:65], v[76:79], off nt
	global_store_dwordx4 v[64:65], v[80:83], off offset:16 nt
	global_store_dwordx4 v[64:65], v[84:87], off offset:2048 nt
	global_store_dwordx4 v[64:65], v[88:91], off offset:2064 nt
	v_pk_fma_f32 v[78:79], v[6:7], v[94:95], v[98:99]
	v_pk_fma_f32 v[76:77], v[4:5], v[92:93], v[96:97]
	v_pk_fma_f32 v[82:83], v[2:3], v[116:117], v[104:105]
	v_pk_fma_f32 v[80:81], v[0:1], v[100:101], v[102:103]
	v_pk_fma_f32 v[86:87], v[14:15], v[112:113], v[108:109]
	v_pk_fma_f32 v[84:85], v[12:13], v[118:119], v[106:107]
	v_pk_fma_f32 v[90:91], v[10:11], v[114:115], v[110:111]
	v_pk_fma_f32 v[88:89], v[8:9], v[120:121], v[124:125]
	global_store_dwordx4 v[62:63], v[76:79], off nt
	global_store_dwordx4 v[62:63], v[80:83], off offset:16 nt
	global_store_dwordx4 v[62:63], v[84:87], off offset:2048 nt
	global_store_dwordx4 v[62:63], v[88:91], off offset:2064 nt
	global_load_dwordx4 v[62:65], v[56:57], off
	s_nop 0
	global_load_dwordx4 v[76:79], v[56:57], off offset:1024
	global_load_dwordx4 v[80:83], v[54:55], off offset:1024
	global_load_dwordx4 v[84:87], v[58:59], off
	global_load_dwordx4 v[88:91], v[58:59], off offset:1024
	global_load_dwordx4 v[92:95], v[60:61], off offset:1024
	global_load_dwordx4 v[96:99], v[54:55], off
	global_load_dwordx4 v[100:103], v[60:61], off
	s_waitcnt vmcnt(7)
	v_lshlrev_b32_e32 v54, 16, v62
	v_and_b32_e32 v55, 0xffff0000, v62
	s_waitcnt vmcnt(5)
	v_lshlrev_b32_e32 v120, 16, v80
	v_and_b32_e32 v121, 0xffff0000, v80
	v_lshlrev_b32_e32 v80, 16, v81
	v_and_b32_e32 v81, 0xffff0000, v81
	s_waitcnt vmcnt(1)
	v_lshlrev_b32_e32 v116, 16, v96
	v_and_b32_e32 v117, 0xffff0000, v96
	v_lshlrev_b32_e32 v96, 16, v97
	v_lshlrev_b32_e32 v119, 16, v99
	v_lshlrev_b32_e32 v118, 16, v98
	v_and_b32_e32 v99, 0xffff0000, v99
	v_and_b32_e32 v98, 0xffff0000, v98
	v_and_b32_e32 v97, 0xffff0000, v97
	s_waitcnt vmcnt(0)
	v_lshlrev_b32_e32 v122, 16, v100
	v_and_b32_e32 v123, 0xffff0000, v100
	v_lshlrev_b32_e32 v100, 16, v101
	v_lshlrev_b32_e32 v125, 16, v103
	v_lshlrev_b32_e32 v124, 16, v102
	v_and_b32_e32 v103, 0xffff0000, v103
	v_and_b32_e32 v102, 0xffff0000, v102
	v_mul_f32_e32 v128, v116, v116
	v_mul_f32_e32 v130, v96, v96
	v_pk_mul_f32 v[132:133], v[98:99], v[98:99]
	v_and_b32_e32 v101, 0xffff0000, v101
	v_lshlrev_b32_e32 v126, 16, v92
	v_and_b32_e32 v127, 0xffff0000, v92
	v_lshlrev_b32_e32 v92, 16, v93
	v_mul_f32_e32 v134, v120, v120
	v_mul_f32_e32 v136, v80, v80
	v_mul_f32_e32 v140, v122, v122
	v_mul_f32_e32 v142, v100, v100
	v_pk_mul_f32 v[144:145], v[102:103], v[102:103]
	v_mov_b32_e32 v152, v118
	v_mov_b32_e32 v153, v98
	v_mov_b32_e32 v98, v119
	v_pk_fma_f32 v[128:129], v[116:117], v[116:117], v[128:129] op_sel_hi:[1,1,0]
	v_pk_fma_f32 v[130:131], v[96:97], v[96:97], v[130:131] op_sel_hi:[1,1,0]
	v_pk_fma_f32 v[118:119], v[118:119], v[118:119], v[132:133]
	v_lshlrev_b32_e32 v104, 16, v82
	v_and_b32_e32 v105, 0xffff0000, v82
	v_lshlrev_b32_e32 v82, 16, v83
	v_and_b32_e32 v83, 0xffff0000, v83
	v_and_b32_e32 v93, 0xffff0000, v93
	v_mul_f32_e32 v146, v126, v126
	v_mul_f32_e32 v148, v92, v92
	v_mov_b32_e32 v154, v124
	v_mov_b32_e32 v155, v102
	v_mov_b32_e32 v102, v125
	v_pk_fma_f32 v[132:133], v[120:121], v[120:121], v[134:135] op_sel_hi:[1,1,0]
	v_pk_fma_f32 v[134:135], v[80:81], v[80:81], v[136:137] op_sel_hi:[1,1,0]
	v_pk_fma_f32 v[136:137], v[122:123], v[122:123], v[140:141] op_sel_hi:[1,1,0]
	v_pk_fma_f32 v[140:141], v[100:101], v[100:101], v[142:143] op_sel_hi:[1,1,0]
	v_pk_fma_f32 v[124:125], v[124:125], v[124:125], v[144:145]
	v_pk_add_f32 v[118:119], v[118:119], v[118:119] op_sel_hi:[0,1]
	v_pk_add_f32 v[128:129], v[128:129], v[130:131]
	v_lshlrev_b32_e32 v114, 16, v94
	v_and_b32_e32 v115, 0xffff0000, v94
	v_lshlrev_b32_e32 v94, 16, v95
	v_and_b32_e32 v95, 0xffff0000, v95
	v_mul_f32_e32 v138, v104, v104
	v_pk_fma_f32 v[142:143], v[126:127], v[126:127], v[146:147] op_sel_hi:[1,1,0]
	v_pk_fma_f32 v[144:145], v[92:93], v[92:93], v[148:149] op_sel_hi:[1,1,0]
	v_mul_f32_e32 v132, v82, v82
	v_mul_f32_e32 v134, v83, v83
	v_pk_add_f32 v[124:125], v[124:125], v[124:125] op_sel_hi:[0,1]
	v_pk_add_f32 v[130:131], v[136:137], v[140:141]
	v_mul_f32_e32 v118, v105, v105
	v_mov_b32_e32 v139, v129
	v_mul_f32_e32 v150, v114, v114
	v_mul_f32_e32 v142, v94, v94
	v_mul_f32_e32 v144, v95, v95
	v_pk_add_f32 v[128:129], v[132:133], v[134:135]
	v_mul_f32_e32 v124, v115, v115
	v_mov_b32_e32 v151, v131
	v_pk_add_f32 v[118:119], v[138:139], v[118:119]
	v_pk_add_f32 v[130:131], v[142:143], v[144:145]
	v_pk_add_f32 v[124:125], v[150:151], v[124:125]
	v_pk_add_f32 v[118:119], v[118:119], v[128:129]
	v_pk_add_f32 v[124:125], v[124:125], v[130:131]
	v_add_f32_e32 v118, v118, v119
	v_add_f32_e32 v119, v124, v125
	ds_bpermute_b32 v124, v66, v118
	ds_bpermute_b32 v125, v66, v119
	v_lshlrev_b32_e32 v56, 16, v63
	v_and_b32_e32 v57, 0xffff0000, v63
	v_lshlrev_b32_e32 v58, 16, v64
	s_waitcnt lgkmcnt(1)
; #define UNPK(V_, lo4, hi4) do { lo4 = (f32x4){bflo((V_).x), bfhi((V_).x), bflo((V_).y), bfhi((V_).y)}; hi4 = (f32x4){bflo((V_).z), bfhi((V_).z), bflo((V_).w), bfhi((V_).w)}; } while (0)
; template <bool FIRST, bool HAS_NEXT, bool CTXSPLIT = false>
; __device__ __forceinline__ void phase_rows(const KArgs& a, int row_begin, int nrows, int CH, const float* mods_cur, int gate_ch, const float* g_post, const float* mods_nxt, int sh_ch, const float* g_pre, int lane, int wave) {
;     ...
;             for (int q = 0; q < 2; ++q) { const int r = r0 + rr + q;
;                 const float* xin = r < MLAT ? a.x + (size_t)r * DM : a.ctx + (size_t)(r - MLAT) * DM;
;                 const bf16r* ay = AY + (size_t)r * DM; ss[q] = 0.f;
; #pragma unroll
;                 for (int jp = 0; jp < 2; ++jp) { const int c8 = 512 * jp + 8 * lane;
;                     if (FIRST) { xv[q][2 * jp] = __builtin_nontemporal_load((const f32x4*)(xin + c8)); xv[q][2 * jp + 1] = __builtin_nontemporal_load((const f32x4*)(xin + c8 + 4)); }
;                     else { const u32x4 xw = *(const u32x4*)(XB + (size_t)r * DM + c8); UNPK(xw, xv[q][2 * jp], xv[q][2 * jp + 1]); }
;     ...
;             for (int o = 1; o < 64; o <<= 1) { ss[0] += __shfl_xor(ss[0], o); ss[1] += __shfl_xor(ss[1], o); }
; #pragma unroll
;             for (int q = 0; q < 2; ++q) { const int r = r0 + rr + q;
;                 const float ry = 1.0f / sqrtf(ss[q] * (1.0f / DM) + EPS); s2[q] = 0.f;
; #pragma unroll
;                 for (int j = 0; j < 4; ++j) { xv[q][j] = xv[q][j] + gg[j] * (yv[q][j] * ry);
;                     s2[q] += (xv[q][j].x * xv[q][j].x + xv[q][j].y * xv[q][j].y) + (xv[q][j].z * xv[q][j].z + xv[q][j].w * xv[q][j].w); }
; #pragma unroll
;                 for (int jp = 0; jp < 2; ++jp) { const int c8 = 512 * jp + 8 * lane; const f32x4 lo4 = xv[q][2 * jp], hi4 = xv[q][2 * jp + 1];
;                     if (HAS_NEXT) { u32x4 xo; xo.x = pk2(lo4.x, lo4.y); xo.y = pk2(lo4.z, lo4.w); xo.z = pk2(hi4.x, hi4.y); xo.w = pk2(hi4.z, hi4.w); *(u32x4*)(XB + (size_t)r * DM + c8) = xo; }
;                     else { *(f32x4*)(a.out + (size_t)r * DM + c8) = lo4; *(f32x4*)(a.out + (size_t)r * DM + c8 + 4) = hi4; } } }
	v_add_f32_e32 v118, v118, v124
	s_waitcnt lgkmcnt(0)
	v_add_f32_e32 v119, v119, v125
	ds_bpermute_b32 v124, v67, v118
	ds_bpermute_b32 v125, v67, v119
	v_and_b32_e32 v59, 0xffff0000, v64
	v_lshlrev_b32_e32 v60, 16, v65
	v_and_b32_e32 v61, 0xffff0000, v65
	s_waitcnt lgkmcnt(1)
	v_add_f32_e32 v118, v118, v124
	s_waitcnt lgkmcnt(0)
	v_add_f32_e32 v119, v119, v125
	ds_bpermute_b32 v124, v68, v118
	ds_bpermute_b32 v125, v68, v119
	v_lshlrev_b32_e32 v62, 16, v76
	v_and_b32_e32 v63, 0xffff0000, v76
	v_lshlrev_b32_e32 v64, 16, v77
	s_waitcnt lgkmcnt(1)
	v_add_f32_e32 v118, v118, v124
	s_waitcnt lgkmcnt(0)
	v_add_f32_e32 v119, v119, v125
	ds_bpermute_b32 v124, v69, v118
	ds_bpermute_b32 v125, v69, v119
	v_and_b32_e32 v65, 0xffff0000, v77
	v_lshlrev_b32_e32 v76, 16, v78
	v_and_b32_e32 v77, 0xffff0000, v78
	s_waitcnt lgkmcnt(1)
	v_add_f32_e32 v118, v118, v124
	s_waitcnt lgkmcnt(0)
	v_add_f32_e32 v119, v119, v125
	ds_bpermute_b32 v124, v70, v118
	ds_bpermute_b32 v125, v70, v119
	v_lshlrev_b32_e32 v78, 16, v79
	v_and_b32_e32 v79, 0xffff0000, v79
	v_lshlrev_b32_e32 v106, 16, v84
	s_waitcnt lgkmcnt(1)
	v_add_f32_e32 v118, v118, v124
	s_waitcnt lgkmcnt(0)
	v_add_f32_e32 v119, v119, v125
	ds_bpermute_b32 v124, v71, v118
	ds_bpermute_b32 v125, v71, v119
	v_and_b32_e32 v107, 0xffff0000, v84
	v_lshlrev_b32_e32 v84, 16, v85
	v_and_b32_e32 v85, 0xffff0000, v85
	s_waitcnt lgkmcnt(1)
	v_add_f32_e32 v118, v118, v124
	s_waitcnt lgkmcnt(0)
	v_add_f32_e32 v119, v119, v125
	v_fmamk_f32 v118, v118, 0x3a800000, v74
	v_fmamk_f32 v119, v119, 0x3a800000, v74
	v_mul_f32_e32 v124, 0x4f800000, v118
	v_cmp_gt_f32_e64 s[0:1], s19, v118
	v_mul_f32_e32 v125, 0x4f800000, v119
	v_cmp_gt_f32_e32 vcc, s19, v119
	v_cndmask_b32_e64 v118, v118, v124, s[0:1]
	v_sqrt_f32_e32 v124, v118
	v_cndmask_b32_e32 v119, v119, v125, vcc
	v_sqrt_f32_e32 v125, v119
	v_lshlrev_b32_e32 v108, 16, v86
	v_add_u32_e32 v128, -1, v124
	v_add_u32_e32 v129, 1, v124
	v_add_u32_e32 v130, -1, v125
	v_fma_f32 v132, -v128, v124, v118
	v_add_u32_e32 v131, 1, v125
	v_fma_f32 v133, -v129, v124, v118
	v_fma_f32 v134, -v130, v125, v119
	v_cmp_ge_f32_e64 s[2:3], 0, v132
	v_fma_f32 v135, -v131, v125, v119
	v_cmp_lt_f32_e64 s[4:5], 0, v133
	v_cndmask_b32_e64 v124, v124, v128, s[2:3]
	v_cmp_ge_f32_e64 s[2:3], 0, v134
	v_cndmask_b32_e64 v124, v124, v129, s[4:5]
	v_mul_f32_e32 v128, 0x37800000, v124
	v_cndmask_b32_e64 v125, v125, v130, s[2:3]
	v_cmp_lt_f32_e64 s[2:3], 0, v135
	v_cndmask_b32_e64 v124, v124, v128, s[0:1]
	v_cmp_class_f32_e64 s[0:1], v118, v75
	v_cndmask_b32_e64 v125, v125, v131, s[2:3]
	v_mul_f32_e32 v129, 0x37800000, v125
	v_cndmask_b32_e32 v125, v125, v129, vcc
	v_cmp_class_f32_e32 vcc, v119, v75
	v_cndmask_b32_e64 v118, v124, v118, s[0:1]
	v_div_scale_f32 v124, s[0:1], v118, v118, 1.0
	v_cndmask_b32_e32 v119, v125, v119, vcc
	v_div_scale_f32 v128, s[0:1], v119, v119, 1.0
	v_rcp_f32_e32 v130, v124
	v_rcp_f32_e32 v131, v128
	v_div_scale_f32 v125, vcc, 1.0, v118, 1.0
	v_fma_f32 v132, -v124, v130, 1.0
	v_fma_f32 v133, -v128, v131, 1.0
	v_fmac_f32_e32 v130, v132, v130
	v_div_scale_f32 v129, s[0:1], 1.0, v119, 1.0
	v_fmac_f32_e32 v131, v133, v131
	v_mul_f32_e32 v132, v125, v130
	v_mul_f32_e32 v133, v129, v131
	v_fma_f32 v134, -v124, v132, v125
	v_fma_f32 v135, -v128, v133, v129
	v_fmac_f32_e32 v132, v134, v130
	v_fmac_f32_e32 v133, v135, v131
	v_fma_f32 v124, -v124, v132, v125
	v_fma_f32 v125, -v128, v133, v129
	v_div_fmas_f32 v124, v124, v130, v132
	s_mov_b64 vcc, s[0:1]
	v_div_fixup_f32 v118, v124, v118, 1.0
	v_div_fmas_f32 v128, v125, v131, v133
	v_pk_mul_f32 v[116:117], v[118:119], v[116:117] op_sel_hi:[0,1]
	v_pk_mul_f32 v[96:97], v[118:119], v[96:97] op_sel_hi:[0,1]
	v_pk_mul_f32 v[124:125], v[118:119], v[152:153] op_sel_hi:[0,1]
	v_pk_mul_f32 v[98:99], v[118:119], v[98:99] op_sel_hi:[0,1]
	v_pk_mul_f32 v[120:121], v[118:119], v[120:121] op_sel_hi:[0,1]
	v_pk_mul_f32 v[80:81], v[118:119], v[80:81] op_sel_hi:[0,1]
	v_pk_mul_f32 v[104:105], v[118:119], v[104:105] op_sel_hi:[0,1]
	v_pk_mul_f32 v[82:83], v[118:119], v[82:83] op_sel_hi:[0,1]
	v_div_fixup_f32 v118, v128, v119, 1.0
	v_pk_fma_f32 v[56:57], v[6:7], v[96:97], v[56:57]
	v_pk_fma_f32 v[54:55], v[4:5], v[116:117], v[54:55]
	v_pk_fma_f32 v[64:65], v[14:15], v[80:81], v[64:65]
	v_pk_fma_f32 v[78:79], v[10:11], v[82:83], v[78:79]
	v_pk_mul_f32 v[80:81], v[118:119], v[122:123] op_sel_hi:[0,1]
	v_pk_mul_f32 v[82:83], v[118:119], v[100:101] op_sel_hi:[0,1]
	v_and_b32_e32 v109, 0xffff0000, v86
	v_lshlrev_b32_e32 v86, 16, v87
	v_and_b32_e32 v87, 0xffff0000, v87
	v_lshlrev_b32_e32 v110, 16, v88
	v_and_b32_e32 v111, 0xffff0000, v88
	v_lshlrev_b32_e32 v88, 16, v89
	v_and_b32_e32 v89, 0xffff0000, v89
	v_lshlrev_b32_e32 v112, 16, v90
	v_and_b32_e32 v113, 0xffff0000, v90
	v_lshlrev_b32_e32 v90, 16, v91
	v_and_b32_e32 v91, 0xffff0000, v91
	v_pk_fma_f32 v[60:61], v[2:3], v[98:99], v[60:61]
	v_pk_fma_f32 v[58:59], v[0:1], v[124:125], v[58:59]
	v_pk_fma_f32 v[62:63], v[12:13], v[120:121], v[62:63]
	v_pk_fma_f32 v[76:77], v[8:9], v[104:105], v[76:77]
	v_pk_mul_f32 v[96:97], v[118:119], v[154:155] op_sel_hi:[0,1]
	v_pk_mul_f32 v[98:99], v[118:119], v[102:103] op_sel_hi:[0,1]
	v_pk_mul_f32 v[100:101], v[118:119], v[126:127] op_sel_hi:[0,1]
	v_pk_mul_f32 v[92:93], v[118:119], v[92:93] op_sel_hi:[0,1]
	v_pk_mul_f32 v[102:103], v[118:119], v[114:115] op_sel_hi:[0,1]
	v_pk_mul_f32 v[94:95], v[118:119], v[94:95] op_sel_hi:[0,1]
	global_store_dwordx4 v[52:53], v[54:57], off nt
	global_store_dwordx4 v[52:53], v[58:61], off offset:16 nt
	global_store_dwordx4 v[52:53], v[62:65], off offset:2048 nt
	global_store_dwordx4 v[52:53], v[76:79], off offset:2064 nt
	v_pk_fma_f32 v[54:55], v[6:7], v[82:83], v[84:85]
	v_pk_fma_f32 v[52:53], v[4:5], v[80:81], v[106:107]
	v_pk_fma_f32 v[58:59], v[2:3], v[98:99], v[86:87]
	v_pk_fma_f32 v[56:57], v[0:1], v[96:97], v[108:109]
	v_pk_fma_f32 v[62:63], v[14:15], v[92:93], v[88:89]
	v_pk_fma_f32 v[60:61], v[12:13], v[100:101], v[110:111]
	v_pk_fma_f32 v[78:79], v[10:11], v[94:95], v[90:91]
	v_pk_fma_f32 v[76:77], v[8:9], v[102:103], v[112:113]
	global_store_dwordx4 v[50:51], v[52:55], off nt
	global_store_dwordx4 v[50:51], v[56:59], off offset:16 nt
	global_store_dwordx4 v[50:51], v[60:63], off offset:2048 nt
	global_store_dwordx4 v[50:51], v[76:79], off offset:2064 nt
	global_load_dwordx4 v[50:53], v[42:43], off
	s_nop 0
	global_load_dwordx4 v[54:57], v[42:43], off offset:1024
	global_load_dwordx4 v[58:61], v[46:47], off offset:1024
	global_load_dwordx4 v[62:65], v[44:45], off
	global_load_dwordx4 v[76:79], v[44:45], off offset:1024
	global_load_dwordx4 v[80:83], v[48:49], off offset:1024
	global_load_dwordx4 v[84:87], v[46:47], off
	global_load_dwordx4 v[88:91], v[48:49], off
	s_waitcnt vmcnt(7)
; #define UNPK(V_, lo4, hi4) do { lo4 = (f32x4){bflo((V_).x), bfhi((V_).x), bflo((V_).y), bfhi((V_).y)}; hi4 = (f32x4){bflo((V_).z), bfhi((V_).z), bflo((V_).w), bfhi((V_).w)}; } while (0)
; template <bool FIRST, bool HAS_NEXT, bool CTXSPLIT = false>
; __device__ __forceinline__ void phase_rows(const KArgs& a, int row_begin, int nrows, int CH, const float* mods_cur, int gate_ch, const float* g_post, const float* mods_nxt, int sh_ch, const float* g_pre, int lane, int wave) {
;     ...
;                     else { const u32x4 xw = *(const u32x4*)(XB + (size_t)r * DM + c8); UNPK(xw, xv[q][2 * jp], xv[q][2 * jp + 1]); }
;                     if (CTXSPLIT && r >= MLAT) {
; #pragma unroll
;                         for (int h = 0; h < 2; ++h) { const float* pp = (const float*)a.out + (size_t)(r - MLAT) * DM + c8 + 4 * h; f32x4 acc4 = *(const f32x4*)pp;
; #pragma unroll
;                             for (int ks = 1; ks < KSPLIT; ++ks) acc4 += *(const f32x4*)(pp + (size_t)ks * MCTX * DM);
;                             yv[q][2 * jp + h] = acc4; } }
;                     else { const u32x4 w = *(const u32x4*)(ay + c8); UNPK(w, yv[q][2 * jp], yv[q][2 * jp + 1]); } } }
; #pragma unroll
;             for (int q = 0; q < 2; ++q)
; #pragma unroll
;                 for (int j = 0; j < 4; ++j) ss[q] += (yv[q][j].x * yv[q][j].x + yv[q][j].y * yv[q][j].y) + (yv[q][j].z * yv[q][j].z + yv[q][j].w * yv[q][j].w);
; #pragma unroll
;             for (int o = 1; o < 64; o <<= 1) { ss[0] += __shfl_xor(ss[0], o); ss[1] += __shfl_xor(ss[1], o); }
	v_lshlrev_b32_e32 v42, 16, v50
	v_and_b32_e32 v43, 0xffff0000, v50
	s_waitcnt vmcnt(5)
	v_lshlrev_b32_e32 v108, 16, v58
	v_and_b32_e32 v109, 0xffff0000, v58
	v_lshlrev_b32_e32 v58, 16, v59
	v_and_b32_e32 v59, 0xffff0000, v59
	s_waitcnt vmcnt(1)
	v_lshlrev_b32_e32 v104, 16, v84
	v_and_b32_e32 v105, 0xffff0000, v84
	v_lshlrev_b32_e32 v84, 16, v85
	v_lshlrev_b32_e32 v107, 16, v87
	v_lshlrev_b32_e32 v106, 16, v86
	v_and_b32_e32 v87, 0xffff0000, v87
	v_and_b32_e32 v86, 0xffff0000, v86
	v_and_b32_e32 v85, 0xffff0000, v85
	s_waitcnt vmcnt(0)
	v_lshlrev_b32_e32 v110, 16, v88
	v_and_b32_e32 v111, 0xffff0000, v88
	v_lshlrev_b32_e32 v88, 16, v89
	v_lshlrev_b32_e32 v113, 16, v91
	v_lshlrev_b32_e32 v112, 16, v90
	v_and_b32_e32 v91, 0xffff0000, v91
	v_and_b32_e32 v90, 0xffff0000, v90
	v_mul_f32_e32 v116, v104, v104
	v_mul_f32_e32 v118, v84, v84
	v_pk_mul_f32 v[120:121], v[86:87], v[86:87]
	v_and_b32_e32 v89, 0xffff0000, v89
	v_lshlrev_b32_e32 v114, 16, v80
	v_and_b32_e32 v115, 0xffff0000, v80
	v_lshlrev_b32_e32 v80, 16, v81
	v_mul_f32_e32 v122, v108, v108
	v_mul_f32_e32 v124, v58, v58
	v_mul_f32_e32 v128, v110, v110
	v_mul_f32_e32 v130, v88, v88
	v_pk_mul_f32 v[132:133], v[90:91], v[90:91]
	v_mov_b32_e32 v140, v106
	v_mov_b32_e32 v141, v86
	v_mov_b32_e32 v86, v107
	v_pk_fma_f32 v[116:117], v[104:105], v[104:105], v[116:117] op_sel_hi:[1,1,0]
	v_pk_fma_f32 v[118:119], v[84:85], v[84:85], v[118:119] op_sel_hi:[1,1,0]
	v_pk_fma_f32 v[106:107], v[106:107], v[106:107], v[120:121]
	v_lshlrev_b32_e32 v92, 16, v60
	v_and_b32_e32 v93, 0xffff0000, v60
	v_lshlrev_b32_e32 v60, 16, v61
	v_and_b32_e32 v61, 0xffff0000, v61
	v_and_b32_e32 v81, 0xffff0000, v81
	v_mul_f32_e32 v134, v114, v114
	v_mul_f32_e32 v136, v80, v80
	v_mov_b32_e32 v142, v112
	v_mov_b32_e32 v143, v90
	v_mov_b32_e32 v90, v113
	v_pk_fma_f32 v[120:121], v[108:109], v[108:109], v[122:123] op_sel_hi:[1,1,0]
	v_pk_fma_f32 v[122:123], v[58:59], v[58:59], v[124:125] op_sel_hi:[1,1,0]
	v_pk_fma_f32 v[124:125], v[110:111], v[110:111], v[128:129] op_sel_hi:[1,1,0]
	v_pk_fma_f32 v[128:129], v[88:89], v[88:89], v[130:131] op_sel_hi:[1,1,0]
	v_pk_fma_f32 v[112:113], v[112:113], v[112:113], v[132:133]
	v_pk_add_f32 v[106:107], v[106:107], v[106:107] op_sel_hi:[0,1]
	v_pk_add_f32 v[116:117], v[116:117], v[118:119]
	v_lshlrev_b32_e32 v102, 16, v82
	v_and_b32_e32 v103, 0xffff0000, v82
	v_lshlrev_b32_e32 v82, 16, v83
	v_and_b32_e32 v83, 0xffff0000, v83
	v_mul_f32_e32 v126, v92, v92
	v_pk_fma_f32 v[130:131], v[114:115], v[114:115], v[134:135] op_sel_hi:[1,1,0]
	v_pk_fma_f32 v[132:133], v[80:81], v[80:81], v[136:137] op_sel_hi:[1,1,0]
	v_mul_f32_e32 v120, v60, v60
	v_mul_f32_e32 v122, v61, v61
	v_pk_add_f32 v[112:113], v[112:113], v[112:113] op_sel_hi:[0,1]
	v_pk_add_f32 v[118:119], v[124:125], v[128:129]
	v_mul_f32_e32 v106, v93, v93
	v_mov_b32_e32 v127, v117
	v_mul_f32_e32 v138, v102, v102
	v_mul_f32_e32 v130, v82, v82
	v_mul_f32_e32 v132, v83, v83
	v_pk_add_f32 v[116:117], v[120:121], v[122:123]
	v_mul_f32_e32 v112, v103, v103
	v_mov_b32_e32 v139, v119
	v_pk_add_f32 v[106:107], v[126:127], v[106:107]
	v_pk_add_f32 v[118:119], v[130:131], v[132:133]
	v_pk_add_f32 v[112:113], v[138:139], v[112:113]
	v_pk_add_f32 v[106:107], v[106:107], v[116:117]
	v_pk_add_f32 v[112:113], v[112:113], v[118:119]
	v_add_f32_e32 v106, v106, v107
	v_add_f32_e32 v107, v112, v113
	ds_bpermute_b32 v112, v66, v106
	ds_bpermute_b32 v113, v66, v107
	v_lshlrev_b32_e32 v44, 16, v51
	v_and_b32_e32 v45, 0xffff0000, v51
	v_lshlrev_b32_e32 v46, 16, v52
	s_waitcnt lgkmcnt(1)
	v_add_f32_e32 v106, v106, v112
	s_waitcnt lgkmcnt(0)
	v_add_f32_e32 v107, v107, v113
	ds_bpermute_b32 v112, v67, v106
	ds_bpermute_b32 v113, v67, v107
	v_and_b32_e32 v47, 0xffff0000, v52
	v_lshlrev_b32_e32 v48, 16, v53
	v_and_b32_e32 v49, 0xffff0000, v53
	s_waitcnt lgkmcnt(1)
	v_add_f32_e32 v106, v106, v112
	s_waitcnt lgkmcnt(0)
	v_add_f32_e32 v107, v107, v113
	ds_bpermute_b32 v112, v68, v106
	ds_bpermute_b32 v113, v68, v107
	v_lshlrev_b32_e32 v50, 16, v54
	v_and_b32_e32 v51, 0xffff0000, v54
	v_lshlrev_b32_e32 v52, 16, v55
	s_waitcnt lgkmcnt(1)
	v_add_f32_e32 v106, v106, v112
	s_waitcnt lgkmcnt(0)
	v_add_f32_e32 v107, v107, v113
	ds_bpermute_b32 v112, v69, v106
	ds_bpermute_b32 v113, v69, v107
	v_and_b32_e32 v53, 0xffff0000, v55
	v_lshlrev_b32_e32 v54, 16, v56
	v_and_b32_e32 v55, 0xffff0000, v56
	s_waitcnt lgkmcnt(1)
	v_add_f32_e32 v106, v106, v112
	s_waitcnt lgkmcnt(0)
	v_add_f32_e32 v107, v107, v113
	ds_bpermute_b32 v112, v70, v106
	ds_bpermute_b32 v113, v70, v107
	v_lshlrev_b32_e32 v56, 16, v57
	v_and_b32_e32 v57, 0xffff0000, v57
	v_lshlrev_b32_e32 v94, 16, v62
	s_waitcnt lgkmcnt(1)
	v_add_f32_e32 v106, v106, v112
	s_waitcnt lgkmcnt(0)
	v_add_f32_e32 v107, v107, v113
	ds_bpermute_b32 v112, v71, v106
	ds_bpermute_b32 v113, v71, v107
	v_and_b32_e32 v95, 0xffff0000, v62
	v_lshlrev_b32_e32 v62, 16, v63
	v_and_b32_e32 v63, 0xffff0000, v63
	s_waitcnt lgkmcnt(1)
	v_add_f32_e32 v106, v106, v112
	s_waitcnt lgkmcnt(0)
; #define UNPK(V_, lo4, hi4) do { lo4 = (f32x4){bflo((V_).x), bfhi((V_).x), bflo((V_).y), bfhi((V_).y)}; hi4 = (f32x4){bflo((V_).z), bfhi((V_).z), bflo((V_).w), bfhi((V_).w)}; } while (0)
; template <bool FIRST, bool HAS_NEXT, bool CTXSPLIT = false>
; __device__ __forceinline__ void phase_rows(const KArgs& a, int row_begin, int nrows, int CH, const float* mods_cur, int gate_ch, const float* g_post, const float* mods_nxt, int sh_ch, const float* g_pre, int lane, int wave) {
;     ...
;             for (int q = 0; q < 2; ++q) { const int r = r0 + rr + q;
;                 const float* xin = r < MLAT ? a.x + (size_t)r * DM : a.ctx + (size_t)(r - MLAT) * DM;
;                 const bf16r* ay = AY + (size_t)r * DM; ss[q] = 0.f;
; #pragma unroll
;                 for (int jp = 0; jp < 2; ++jp) { const int c8 = 512 * jp + 8 * lane;
;                     if (FIRST) { xv[q][2 * jp] = __builtin_nontemporal_load((const f32x4*)(xin + c8)); xv[q][2 * jp + 1] = __builtin_nontemporal_load((const f32x4*)(xin + c8 + 4)); }
;                     else { const u32x4 xw = *(const u32x4*)(XB + (size_t)r * DM + c8); UNPK(xw, xv[q][2 * jp], xv[q][2 * jp + 1]); }
;     ...
;             for (int q = 0; q < 2; ++q) { const int r = r0 + rr + q;
;                 const float ry = 1.0f / sqrtf(ss[q] * (1.0f / DM) + EPS); s2[q] = 0.f;
; #pragma unroll
;                 for (int j = 0; j < 4; ++j) { xv[q][j] = xv[q][j] + gg[j] * (yv[q][j] * ry);
;                     s2[q] += (xv[q][j].x * xv[q][j].x + xv[q][j].y * xv[q][j].y) + (xv[q][j].z * xv[q][j].z + xv[q][j].w * xv[q][j].w); }
; #pragma unroll
;                 for (int jp = 0; jp < 2; ++jp) { const int c8 = 512 * jp + 8 * lane; const f32x4 lo4 = xv[q][2 * jp], hi4 = xv[q][2 * jp + 1];
;                     if (HAS_NEXT) { u32x4 xo; xo.x = pk2(lo4.x, lo4.y); xo.y = pk2(lo4.z, lo4.w); xo.z = pk2(hi4.x, hi4.y); xo.w = pk2(hi4.z, hi4.w); *(u32x4*)(XB + (size_t)r * DM + c8) = xo; }
;                     else { *(f32x4*)(a.out + (size_t)r * DM + c8) = lo4; *(f32x4*)(a.out + (size_t)r * DM + c8 + 4) = hi4; } } }
	v_add_f32_e32 v107, v107, v113
	v_fmamk_f32 v106, v106, 0x3a800000, v74
	v_fmamk_f32 v107, v107, 0x3a800000, v74
	v_mul_f32_e32 v112, 0x4f800000, v106
	v_cmp_gt_f32_e64 s[0:1], s19, v106
	v_mul_f32_e32 v113, 0x4f800000, v107
	v_cmp_gt_f32_e32 vcc, s19, v107
	v_cndmask_b32_e64 v106, v106, v112, s[0:1]
	v_sqrt_f32_e32 v112, v106
	v_cndmask_b32_e32 v107, v107, v113, vcc
	v_sqrt_f32_e32 v113, v107
	v_lshlrev_b32_e32 v96, 16, v64
	v_add_u32_e32 v116, -1, v112
	v_add_u32_e32 v117, 1, v112
	v_add_u32_e32 v118, -1, v113
	v_fma_f32 v120, -v116, v112, v106
	v_add_u32_e32 v119, 1, v113
	v_fma_f32 v121, -v117, v112, v106
	v_fma_f32 v122, -v118, v113, v107
	v_cmp_ge_f32_e64 s[2:3], 0, v120
	v_fma_f32 v123, -v119, v113, v107
	v_cmp_lt_f32_e64 s[4:5], 0, v121
	v_cndmask_b32_e64 v112, v112, v116, s[2:3]
	v_cmp_ge_f32_e64 s[2:3], 0, v122
	v_cndmask_b32_e64 v112, v112, v117, s[4:5]
	v_mul_f32_e32 v116, 0x37800000, v112
	v_cndmask_b32_e64 v113, v113, v118, s[2:3]
	v_cmp_lt_f32_e64 s[2:3], 0, v123
	v_cndmask_b32_e64 v112, v112, v116, s[0:1]
	v_cmp_class_f32_e64 s[0:1], v106, v75
	v_cndmask_b32_e64 v113, v113, v119, s[2:3]
	v_mul_f32_e32 v117, 0x37800000, v113
	v_cndmask_b32_e32 v113, v113, v117, vcc
	v_cmp_class_f32_e32 vcc, v107, v75
	v_cndmask_b32_e64 v106, v112, v106, s[0:1]
	v_div_scale_f32 v112, s[0:1], v106, v106, 1.0
	v_cndmask_b32_e32 v107, v113, v107, vcc
	v_div_scale_f32 v116, s[0:1], v107, v107, 1.0
	v_rcp_f32_e32 v118, v112
	v_rcp_f32_e32 v119, v116
	v_div_scale_f32 v113, vcc, 1.0, v106, 1.0
	v_fma_f32 v120, -v112, v118, 1.0
	v_fma_f32 v121, -v116, v119, 1.0
	v_fmac_f32_e32 v118, v120, v118
	v_div_scale_f32 v117, s[0:1], 1.0, v107, 1.0
	v_fmac_f32_e32 v119, v121, v119
	v_mul_f32_e32 v120, v113, v118
	v_mul_f32_e32 v121, v117, v119
	v_fma_f32 v122, -v112, v120, v113
	v_fma_f32 v123, -v116, v121, v117
	v_fmac_f32_e32 v120, v122, v118
	v_fmac_f32_e32 v121, v123, v119
	v_fma_f32 v112, -v112, v120, v113
	v_fma_f32 v113, -v116, v121, v117
	v_div_fmas_f32 v112, v112, v118, v120
	s_mov_b64 vcc, s[0:1]
	v_div_fixup_f32 v106, v112, v106, 1.0
	v_div_fmas_f32 v116, v113, v119, v121
	v_pk_mul_f32 v[104:105], v[106:107], v[104:105] op_sel_hi:[0,1]
	v_pk_mul_f32 v[84:85], v[106:107], v[84:85] op_sel_hi:[0,1]
	v_pk_mul_f32 v[112:113], v[106:107], v[140:141] op_sel_hi:[0,1]
	v_pk_mul_f32 v[86:87], v[106:107], v[86:87] op_sel_hi:[0,1]
	v_pk_mul_f32 v[108:109], v[106:107], v[108:109] op_sel_hi:[0,1]
	v_pk_mul_f32 v[58:59], v[106:107], v[58:59] op_sel_hi:[0,1]
	v_pk_mul_f32 v[92:93], v[106:107], v[92:93] op_sel_hi:[0,1]
	v_pk_mul_f32 v[60:61], v[106:107], v[60:61] op_sel_hi:[0,1]
	v_div_fixup_f32 v106, v116, v107, 1.0
	v_pk_fma_f32 v[44:45], v[6:7], v[84:85], v[44:45]
	v_pk_fma_f32 v[42:43], v[4:5], v[104:105], v[42:43]
	v_pk_fma_f32 v[52:53], v[14:15], v[58:59], v[52:53]
	v_pk_fma_f32 v[56:57], v[10:11], v[60:61], v[56:57]
	v_pk_mul_f32 v[58:59], v[106:107], v[110:111] op_sel_hi:[0,1]
	v_pk_mul_f32 v[60:61], v[106:107], v[88:89] op_sel_hi:[0,1]
	v_and_b32_e32 v97, 0xffff0000, v64
	v_lshlrev_b32_e32 v64, 16, v65
	v_and_b32_e32 v65, 0xffff0000, v65
	v_lshlrev_b32_e32 v98, 16, v76
	v_and_b32_e32 v99, 0xffff0000, v76
	v_lshlrev_b32_e32 v76, 16, v77
	v_and_b32_e32 v77, 0xffff0000, v77
	v_lshlrev_b32_e32 v100, 16, v78
	v_and_b32_e32 v101, 0xffff0000, v78
	v_lshlrev_b32_e32 v78, 16, v79
	v_and_b32_e32 v79, 0xffff0000, v79
	v_pk_fma_f32 v[48:49], v[2:3], v[86:87], v[48:49]
	v_pk_fma_f32 v[46:47], v[0:1], v[112:113], v[46:47]
	v_pk_fma_f32 v[50:51], v[12:13], v[108:109], v[50:51]
	v_pk_fma_f32 v[54:55], v[8:9], v[92:93], v[54:55]
	v_pk_mul_f32 v[84:85], v[106:107], v[142:143] op_sel_hi:[0,1]
	v_pk_mul_f32 v[86:87], v[106:107], v[90:91] op_sel_hi:[0,1]
	v_pk_mul_f32 v[88:89], v[106:107], v[114:115] op_sel_hi:[0,1]
	v_pk_mul_f32 v[80:81], v[106:107], v[80:81] op_sel_hi:[0,1]
	v_pk_mul_f32 v[90:91], v[106:107], v[102:103] op_sel_hi:[0,1]
	v_pk_mul_f32 v[82:83], v[106:107], v[82:83] op_sel_hi:[0,1]
	global_store_dwordx4 v[40:41], v[42:45], off nt
	global_store_dwordx4 v[40:41], v[46:49], off offset:16 nt
	global_store_dwordx4 v[40:41], v[50:53], off offset:2048 nt
	global_store_dwordx4 v[40:41], v[54:57], off offset:2064 nt
	v_pk_fma_f32 v[42:43], v[6:7], v[60:61], v[62:63]
	v_pk_fma_f32 v[40:41], v[4:5], v[58:59], v[94:95]
	v_pk_fma_f32 v[46:47], v[2:3], v[86:87], v[64:65]
	v_pk_fma_f32 v[44:45], v[0:1], v[84:85], v[96:97]
	v_pk_fma_f32 v[50:51], v[14:15], v[80:81], v[76:77]
	v_pk_fma_f32 v[48:49], v[12:13], v[88:89], v[98:99]
	v_pk_fma_f32 v[54:55], v[10:11], v[82:83], v[78:79]
	v_pk_fma_f32 v[52:53], v[8:9], v[90:91], v[100:101]
	global_store_dwordx4 v[38:39], v[40:43], off nt
	global_store_dwordx4 v[38:39], v[44:47], off offset:16 nt
	global_store_dwordx4 v[38:39], v[48:51], off offset:2048 nt
	global_store_dwordx4 v[38:39], v[52:55], off offset:2064 nt
	global_load_dwordx4 v[38:41], v[34:35], off
	s_nop 0
	global_load_dwordx4 v[42:45], v[34:35], off offset:1024
	global_load_dwordx4 v[46:49], v[36:37], off offset:1024
	global_load_dwordx4 v[50:53], v[30:31], off
	global_load_dwordx4 v[54:57], v[30:31], off offset:1024
	global_load_dwordx4 v[58:61], v[32:33], off offset:1024
	global_load_dwordx4 v[62:65], v[36:37], off
	global_load_dwordx4 v[76:79], v[32:33], off
	s_waitcnt vmcnt(7)
	v_lshlrev_b32_e32 v30, 16, v38
	v_and_b32_e32 v31, 0xffff0000, v38
	s_waitcnt vmcnt(5)
	v_lshlrev_b32_e32 v96, 16, v46
	v_and_b32_e32 v97, 0xffff0000, v46
	v_lshlrev_b32_e32 v46, 16, v47
	v_and_b32_e32 v47, 0xffff0000, v47
	s_waitcnt vmcnt(1)
	v_lshlrev_b32_e32 v92, 16, v62
	v_and_b32_e32 v93, 0xffff0000, v62
	v_lshlrev_b32_e32 v62, 16, v63
	v_lshlrev_b32_e32 v95, 16, v65
	v_lshlrev_b32_e32 v94, 16, v64
	v_and_b32_e32 v65, 0xffff0000, v65
	v_and_b32_e32 v64, 0xffff0000, v64
	v_and_b32_e32 v63, 0xffff0000, v63
	s_waitcnt vmcnt(0)
; #define UNPK(V_, lo4, hi4) do { lo4 = (f32x4){bflo((V_).x), bfhi((V_).x), bflo((V_).y), bfhi((V_).y)}; hi4 = (f32x4){bflo((V_).z), bfhi((V_).z), bflo((V_).w), bfhi((V_).w)}; } while (0)
; template <bool FIRST, bool HAS_NEXT, bool CTXSPLIT = false>
; __device__ __forceinline__ void phase_rows(const KArgs& a, int row_begin, int nrows, int CH, const float* mods_cur, int gate_ch, const float* g_post, const float* mods_nxt, int sh_ch, const float* g_pre, int lane, int wave) {
;     ...
;             for (int q = 0; q < 2; ++q) { const int r = r0 + rr + q;
;                 const float* xin = r < MLAT ? a.x + (size_t)r * DM : a.ctx + (size_t)(r - MLAT) * DM;
;                 const bf16r* ay = AY + (size_t)r * DM; ss[q] = 0.f;
; #pragma unroll
;                 for (int jp = 0; jp < 2; ++jp) { const int c8 = 512 * jp + 8 * lane;
;                     if (FIRST) { xv[q][2 * jp] = __builtin_nontemporal_load((const f32x4*)(xin + c8)); xv[q][2 * jp + 1] = __builtin_nontemporal_load((const f32x4*)(xin + c8 + 4)); }
;                     else { const u32x4 xw = *(const u32x4*)(XB + (size_t)r * DM + c8); UNPK(xw, xv[q][2 * jp], xv[q][2 * jp + 1]); }
;                     if (CTXSPLIT && r >= MLAT) {
; #pragma unroll
;                         for (int h = 0; h < 2; ++h) { const float* pp = (const float*)a.out + (size_t)(r - MLAT) * DM + c8 + 4 * h; f32x4 acc4 = *(const f32x4*)pp;
; #pragma unroll
;                             for (int ks = 1; ks < KSPLIT; ++ks) acc4 += *(const f32x4*)(pp + (size_t)ks * MCTX * DM);
;                             yv[q][2 * jp + h] = acc4; } }
;                     else { const u32x4 w = *(const u32x4*)(ay + c8); UNPK(w, yv[q][2 * jp], yv[q][2 * jp + 1]); } } }
; #pragma unroll
;             for (int q = 0; q < 2; ++q)
; #pragma unroll
;                 for (int j = 0; j < 4; ++j) ss[q] += (yv[q][j].x * yv[q][j].x + yv[q][j].y * yv[q][j].y) + (yv[q][j].z * yv[q][j].z + yv[q][j].w * yv[q][j].w);
; #pragma unroll
;             for (int o = 1; o < 64; o <<= 1) { ss[0] += __shfl_xor(ss[0], o); ss[1] += __shfl_xor(ss[1], o); }
	v_lshlrev_b32_e32 v98, 16, v76
	v_and_b32_e32 v99, 0xffff0000, v76
	v_lshlrev_b32_e32 v76, 16, v77
	v_lshlrev_b32_e32 v101, 16, v79
	v_lshlrev_b32_e32 v100, 16, v78
	v_and_b32_e32 v79, 0xffff0000, v79
	v_and_b32_e32 v78, 0xffff0000, v78
	v_mul_f32_e32 v104, v92, v92
	v_mul_f32_e32 v106, v62, v62
	v_pk_mul_f32 v[108:109], v[64:65], v[64:65]
	v_and_b32_e32 v77, 0xffff0000, v77
	v_lshlrev_b32_e32 v102, 16, v58
	v_and_b32_e32 v103, 0xffff0000, v58
	v_lshlrev_b32_e32 v58, 16, v59
	v_mul_f32_e32 v110, v96, v96
	v_mul_f32_e32 v112, v46, v46
	v_mul_f32_e32 v116, v98, v98
	v_mul_f32_e32 v118, v76, v76
	v_pk_mul_f32 v[120:121], v[78:79], v[78:79]
	v_mov_b32_e32 v128, v94
	v_mov_b32_e32 v129, v64
	v_mov_b32_e32 v64, v95
	v_pk_fma_f32 v[104:105], v[92:93], v[92:93], v[104:105] op_sel_hi:[1,1,0]
	v_pk_fma_f32 v[106:107], v[62:63], v[62:63], v[106:107] op_sel_hi:[1,1,0]
	v_pk_fma_f32 v[94:95], v[94:95], v[94:95], v[108:109]
	v_lshlrev_b32_e32 v80, 16, v48
	v_and_b32_e32 v81, 0xffff0000, v48
	v_lshlrev_b32_e32 v48, 16, v49
	v_and_b32_e32 v49, 0xffff0000, v49
	v_and_b32_e32 v59, 0xffff0000, v59
	v_mul_f32_e32 v122, v102, v102
	v_mul_f32_e32 v124, v58, v58
	v_mov_b32_e32 v130, v100
	v_mov_b32_e32 v131, v78
	v_mov_b32_e32 v78, v101
	v_pk_fma_f32 v[108:109], v[96:97], v[96:97], v[110:111] op_sel_hi:[1,1,0]
	v_pk_fma_f32 v[110:111], v[46:47], v[46:47], v[112:113] op_sel_hi:[1,1,0]
	v_pk_fma_f32 v[112:113], v[98:99], v[98:99], v[116:117] op_sel_hi:[1,1,0]
	v_pk_fma_f32 v[116:117], v[76:77], v[76:77], v[118:119] op_sel_hi:[1,1,0]
	v_pk_fma_f32 v[100:101], v[100:101], v[100:101], v[120:121]
	v_pk_add_f32 v[94:95], v[94:95], v[94:95] op_sel_hi:[0,1]
	v_pk_add_f32 v[104:105], v[104:105], v[106:107]
	v_lshlrev_b32_e32 v90, 16, v60
	v_and_b32_e32 v91, 0xffff0000, v60
	v_lshlrev_b32_e32 v60, 16, v61
	v_and_b32_e32 v61, 0xffff0000, v61
	v_mul_f32_e32 v114, v80, v80
	v_pk_fma_f32 v[118:119], v[102:103], v[102:103], v[122:123] op_sel_hi:[1,1,0]
	v_pk_fma_f32 v[120:121], v[58:59], v[58:59], v[124:125] op_sel_hi:[1,1,0]
	v_mul_f32_e32 v108, v48, v48
	v_mul_f32_e32 v110, v49, v49
	v_pk_add_f32 v[100:101], v[100:101], v[100:101] op_sel_hi:[0,1]
	v_pk_add_f32 v[106:107], v[112:113], v[116:117]
	v_mul_f32_e32 v94, v81, v81
	v_mov_b32_e32 v115, v105
	v_mul_f32_e32 v126, v90, v90
	v_mul_f32_e32 v118, v60, v60
	v_mul_f32_e32 v120, v61, v61
	v_pk_add_f32 v[104:105], v[108:109], v[110:111]
	v_mul_f32_e32 v100, v91, v91
	v_mov_b32_e32 v127, v107
	v_pk_add_f32 v[94:95], v[114:115], v[94:95]
	v_pk_add_f32 v[106:107], v[118:119], v[120:121]
	v_pk_add_f32 v[100:101], v[126:127], v[100:101]
	v_pk_add_f32 v[94:95], v[94:95], v[104:105]
	v_pk_add_f32 v[100:101], v[100:101], v[106:107]
	v_add_f32_e32 v94, v94, v95
	v_add_f32_e32 v95, v100, v101
	ds_bpermute_b32 v100, v66, v94
	ds_bpermute_b32 v101, v66, v95
	v_lshlrev_b32_e32 v32, 16, v39
	v_and_b32_e32 v33, 0xffff0000, v39
	v_lshlrev_b32_e32 v34, 16, v40
	s_waitcnt lgkmcnt(1)
	v_add_f32_e32 v94, v94, v100
	s_waitcnt lgkmcnt(0)
	v_add_f32_e32 v95, v95, v101
	ds_bpermute_b32 v100, v67, v94
	ds_bpermute_b32 v101, v67, v95
	v_and_b32_e32 v35, 0xffff0000, v40
	v_lshlrev_b32_e32 v36, 16, v41
	v_and_b32_e32 v37, 0xffff0000, v41
	s_waitcnt lgkmcnt(1)
	v_add_f32_e32 v94, v94, v100
	s_waitcnt lgkmcnt(0)
	v_add_f32_e32 v95, v95, v101
	ds_bpermute_b32 v100, v68, v94
	ds_bpermute_b32 v101, v68, v95
	v_lshlrev_b32_e32 v38, 16, v42
	v_and_b32_e32 v39, 0xffff0000, v42
	v_lshlrev_b32_e32 v40, 16, v43
	s_waitcnt lgkmcnt(1)
	v_add_f32_e32 v94, v94, v100
	s_waitcnt lgkmcnt(0)
	v_add_f32_e32 v95, v95, v101
	ds_bpermute_b32 v100, v69, v94
	ds_bpermute_b32 v101, v69, v95
	v_and_b32_e32 v41, 0xffff0000, v43
	v_lshlrev_b32_e32 v42, 16, v44
	v_and_b32_e32 v43, 0xffff0000, v44
	s_waitcnt lgkmcnt(1)
	v_add_f32_e32 v94, v94, v100
	s_waitcnt lgkmcnt(0)
	v_add_f32_e32 v95, v95, v101
	ds_bpermute_b32 v100, v70, v94
	ds_bpermute_b32 v101, v70, v95
	v_lshlrev_b32_e32 v44, 16, v45
	v_and_b32_e32 v45, 0xffff0000, v45
	v_lshlrev_b32_e32 v82, 16, v50
	s_waitcnt lgkmcnt(1)
	v_add_f32_e32 v94, v94, v100
	s_waitcnt lgkmcnt(0)
	v_add_f32_e32 v95, v95, v101
	ds_bpermute_b32 v100, v71, v94
	ds_bpermute_b32 v101, v71, v95
	v_and_b32_e32 v83, 0xffff0000, v50
	v_lshlrev_b32_e32 v50, 16, v51
	v_and_b32_e32 v51, 0xffff0000, v51
	s_waitcnt lgkmcnt(1)
	v_add_f32_e32 v94, v94, v100
	s_waitcnt lgkmcnt(0)
; template <bool FIRST, bool HAS_NEXT, bool CTXSPLIT = false>
; __device__ __forceinline__ void phase_rows(const KArgs& a, int row_begin, int nrows, int CH, const float* mods_cur, int gate_ch, const float* g_post, const float* mods_nxt, int sh_ch, const float* g_pre, int lane, int wave) {
;     ...
;             for (int q = 0; q < 2; ++q) { const int r = r0 + rr + q;
;                 const float ry = 1.0f / sqrtf(ss[q] * (1.0f / DM) + EPS); s2[q] = 0.f;
; #pragma unroll
;                 for (int j = 0; j < 4; ++j) { xv[q][j] = xv[q][j] + gg[j] * (yv[q][j] * ry);
;                     s2[q] += (xv[q][j].x * xv[q][j].x + xv[q][j].y * xv[q][j].y) + (xv[q][j].z * xv[q][j].z + xv[q][j].w * xv[q][j].w); }
; #pragma unroll
;                 for (int jp = 0; jp < 2; ++jp) { const int c8 = 512 * jp + 8 * lane; const f32x4 lo4 = xv[q][2 * jp], hi4 = xv[q][2 * jp + 1];
;                     if (HAS_NEXT) { u32x4 xo; xo.x = pk2(lo4.x, lo4.y); xo.y = pk2(lo4.z, lo4.w); xo.z = pk2(hi4.x, hi4.y); xo.w = pk2(hi4.z, hi4.w); *(u32x4*)(XB + (size_t)r * DM + c8) = xo; }
;                     else { *(f32x4*)(a.out + (size_t)r * DM + c8) = lo4; *(f32x4*)(a.out + (size_t)r * DM + c8 + 4) = hi4; } } }
	v_add_f32_e32 v95, v95, v101
	v_fmamk_f32 v94, v94, 0x3a800000, v74
	v_fmamk_f32 v95, v95, 0x3a800000, v74
	v_mul_f32_e32 v100, 0x4f800000, v94
	v_cmp_gt_f32_e64 s[0:1], s19, v94
	v_mul_f32_e32 v101, 0x4f800000, v95
	v_cmp_gt_f32_e32 vcc, s19, v95
	v_cndmask_b32_e64 v94, v94, v100, s[0:1]
	v_sqrt_f32_e32 v100, v94
	v_cndmask_b32_e32 v95, v95, v101, vcc
	v_sqrt_f32_e32 v101, v95
	v_lshlrev_b32_e32 v84, 16, v52
	v_add_u32_e32 v104, -1, v100
	v_add_u32_e32 v105, 1, v100
	v_add_u32_e32 v106, -1, v101
	v_fma_f32 v108, -v104, v100, v94
	v_add_u32_e32 v107, 1, v101
	v_fma_f32 v109, -v105, v100, v94
	v_fma_f32 v110, -v106, v101, v95
	v_cmp_ge_f32_e64 s[2:3], 0, v108
	v_fma_f32 v111, -v107, v101, v95
	v_cmp_lt_f32_e64 s[4:5], 0, v109
	v_cndmask_b32_e64 v100, v100, v104, s[2:3]
	v_cmp_ge_f32_e64 s[2:3], 0, v110
	v_cndmask_b32_e64 v100, v100, v105, s[4:5]
	v_mul_f32_e32 v104, 0x37800000, v100
	v_cndmask_b32_e64 v101, v101, v106, s[2:3]
	v_cmp_lt_f32_e64 s[2:3], 0, v111
	v_cndmask_b32_e64 v100, v100, v104, s[0:1]
	v_cmp_class_f32_e64 s[0:1], v94, v75
	v_cndmask_b32_e64 v101, v101, v107, s[2:3]
	v_mul_f32_e32 v105, 0x37800000, v101
	v_cndmask_b32_e32 v101, v101, v105, vcc
	v_cmp_class_f32_e32 vcc, v95, v75
	v_cndmask_b32_e64 v94, v100, v94, s[0:1]
	v_div_scale_f32 v100, s[0:1], v94, v94, 1.0
	v_cndmask_b32_e32 v95, v101, v95, vcc
	v_div_scale_f32 v104, s[0:1], v95, v95, 1.0
	v_rcp_f32_e32 v106, v100
	v_rcp_f32_e32 v107, v104
	v_div_scale_f32 v101, vcc, 1.0, v94, 1.0
	v_fma_f32 v108, -v100, v106, 1.0
	v_fma_f32 v109, -v104, v107, 1.0
	v_fmac_f32_e32 v106, v108, v106
	v_div_scale_f32 v105, s[0:1], 1.0, v95, 1.0
	v_fmac_f32_e32 v107, v109, v107
	v_mul_f32_e32 v108, v101, v106
	v_mul_f32_e32 v109, v105, v107
	v_fma_f32 v110, -v100, v108, v101
	v_fma_f32 v111, -v104, v109, v105
	v_fmac_f32_e32 v108, v110, v106
	v_fmac_f32_e32 v109, v111, v107
	v_fma_f32 v100, -v100, v108, v101
	v_fma_f32 v101, -v104, v109, v105
	v_div_fmas_f32 v100, v100, v106, v108
	s_mov_b64 vcc, s[0:1]
	v_div_fixup_f32 v94, v100, v94, 1.0
	v_div_fmas_f32 v104, v101, v107, v109
	v_pk_mul_f32 v[92:93], v[94:95], v[92:93] op_sel_hi:[0,1]
	v_pk_mul_f32 v[62:63], v[94:95], v[62:63] op_sel_hi:[0,1]
	v_pk_mul_f32 v[100:101], v[94:95], v[128:129] op_sel_hi:[0,1]
	v_pk_mul_f32 v[64:65], v[94:95], v[64:65] op_sel_hi:[0,1]
	v_pk_mul_f32 v[96:97], v[94:95], v[96:97] op_sel_hi:[0,1]
	v_pk_mul_f32 v[46:47], v[94:95], v[46:47] op_sel_hi:[0,1]
	v_pk_mul_f32 v[80:81], v[94:95], v[80:81] op_sel_hi:[0,1]
	v_pk_mul_f32 v[48:49], v[94:95], v[48:49] op_sel_hi:[0,1]
	v_div_fixup_f32 v94, v104, v95, 1.0
	v_pk_fma_f32 v[40:41], v[14:15], v[46:47], v[40:41]
	v_pk_fma_f32 v[44:45], v[10:11], v[48:49], v[44:45]
	v_pk_mul_f32 v[46:47], v[94:95], v[98:99] op_sel_hi:[0,1]
	v_pk_mul_f32 v[48:49], v[94:95], v[76:77] op_sel_hi:[0,1]
	v_and_b32_e32 v85, 0xffff0000, v52
	v_lshlrev_b32_e32 v52, 16, v53
	v_and_b32_e32 v53, 0xffff0000, v53
	v_lshlrev_b32_e32 v86, 16, v54
	v_and_b32_e32 v87, 0xffff0000, v54
	v_lshlrev_b32_e32 v54, 16, v55
	v_and_b32_e32 v55, 0xffff0000, v55
	v_lshlrev_b32_e32 v88, 16, v56
	v_and_b32_e32 v89, 0xffff0000, v56
	v_lshlrev_b32_e32 v56, 16, v57
	v_and_b32_e32 v57, 0xffff0000, v57
	v_pk_fma_f32 v[32:33], v[6:7], v[62:63], v[32:33]
	v_pk_fma_f32 v[30:31], v[4:5], v[92:93], v[30:31]
	v_pk_fma_f32 v[36:37], v[2:3], v[64:65], v[36:37]
	v_pk_mul_f32 v[62:63], v[94:95], v[130:131] op_sel_hi:[0,1]
	v_pk_mul_f32 v[64:65], v[94:95], v[78:79] op_sel_hi:[0,1]
	v_pk_mul_f32 v[76:77], v[94:95], v[102:103] op_sel_hi:[0,1]
	v_pk_mul_f32 v[58:59], v[94:95], v[58:59] op_sel_hi:[0,1]
	v_pk_mul_f32 v[78:79], v[94:95], v[90:91] op_sel_hi:[0,1]
	v_pk_mul_f32 v[60:61], v[94:95], v[60:61] op_sel_hi:[0,1]
	v_pk_fma_f32 v[6:7], v[6:7], v[48:49], v[50:51]
	v_pk_fma_f32 v[4:5], v[4:5], v[46:47], v[82:83]
	v_pk_fma_f32 v[34:35], v[0:1], v[100:101], v[34:35]
	v_pk_fma_f32 v[38:39], v[12:13], v[96:97], v[38:39]
	v_pk_fma_f32 v[42:43], v[8:9], v[80:81], v[42:43]
	global_store_dwordx4 v[28:29], v[30:33], off nt
	global_store_dwordx4 v[28:29], v[34:37], off offset:16 nt
	global_store_dwordx4 v[28:29], v[38:41], off offset:2048 nt
	global_store_dwordx4 v[28:29], v[42:45], off offset:2064 nt
	v_pk_fma_f32 v[2:3], v[2:3], v[64:65], v[52:53]
	v_pk_fma_f32 v[0:1], v[0:1], v[62:63], v[84:85]
	v_pk_fma_f32 v[14:15], v[14:15], v[58:59], v[54:55]
	v_pk_fma_f32 v[12:13], v[12:13], v[76:77], v[86:87]
	v_pk_fma_f32 v[10:11], v[10:11], v[60:61], v[56:57]
	v_pk_fma_f32 v[8:9], v[8:9], v[78:79], v[88:89]
	global_store_dwordx4 v[26:27], v[4:7], off nt
	global_store_dwordx4 v[26:27], v[0:3], off offset:16 nt
	global_store_dwordx4 v[26:27], v[12:15], off offset:2048 nt
	global_store_dwordx4 v[26:27], v[8:11], off offset:2064 nt
	s_cbranch_scc1 .LBB0_1185
